# phase-6 stores made write-through (sc1) so the following grid-barrier release write-back finds the L2 clean
# baseline (speedup 1.0000x reference)
.Lp6_A_nopf:
	s_lshl_b32 s4, s2, 12
	s_add_u32 s16, s26, s4
	s_addc_u32 s17, s27, 0
	s_lshl_b32 s4, s2, 13
	s_add_u32 s14, s22, s4
	s_addc_u32 s15, s23, 0
	v_lshlrev_b32_e32 v172, 16, v76
	v_and_b32_e32 v173, 0xffff0000, v76
	v_lshlrev_b32_e32 v174, 16, v77
	v_and_b32_e32 v175, 0xffff0000, v77
	v_lshlrev_b32_e32 v176, 16, v78
	v_and_b32_e32 v177, 0xffff0000, v78
	v_lshlrev_b32_e32 v178, 16, v79
	v_and_b32_e32 v179, 0xffff0000, v79
	v_lshlrev_b32_e32 v180, 16, v80
	v_and_b32_e32 v181, 0xffff0000, v80
	v_lshlrev_b32_e32 v182, 16, v81
	v_and_b32_e32 v183, 0xffff0000, v81
	v_lshlrev_b32_e32 v184, 16, v82
	v_and_b32_e32 v185, 0xffff0000, v82
	v_lshlrev_b32_e32 v186, 16, v83
	v_and_b32_e32 v187, 0xffff0000, v83
	v_lshlrev_b32_e32 v188, 16, v84
	v_and_b32_e32 v189, 0xffff0000, v84
	v_lshlrev_b32_e32 v190, 16, v85
	v_and_b32_e32 v191, 0xffff0000, v85
	v_lshlrev_b32_e32 v192, 16, v86
	v_and_b32_e32 v193, 0xffff0000, v86
	v_lshlrev_b32_e32 v194, 16, v87
	v_and_b32_e32 v195, 0xffff0000, v87
	v_lshlrev_b32_e32 v196, 16, v88
	v_and_b32_e32 v197, 0xffff0000, v88
	v_lshlrev_b32_e32 v198, 16, v89
	v_and_b32_e32 v199, 0xffff0000, v89
	v_lshlrev_b32_e32 v200, 16, v90
	v_and_b32_e32 v201, 0xffff0000, v90
	v_lshlrev_b32_e32 v202, 16, v91
	v_and_b32_e32 v203, 0xffff0000, v91
	v_mul_f32_e32 v206, v172, v172
	v_mul_f32_e32 v207, v173, v173
	v_mul_f32_e32 v210, v174, v174
	v_mul_f32_e32 v211, v175, v175
	v_fmac_f32_e32 v206, v176, v176
	v_fmac_f32_e32 v207, v177, v177
	v_fmac_f32_e32 v210, v178, v178
	v_fmac_f32_e32 v211, v179, v179
	v_fmac_f32_e32 v206, v180, v180
	v_fmac_f32_e32 v207, v181, v181
	v_fmac_f32_e32 v210, v182, v182
	v_fmac_f32_e32 v211, v183, v183
	v_fmac_f32_e32 v206, v184, v184
	v_fmac_f32_e32 v207, v185, v185
	v_fmac_f32_e32 v210, v186, v186
	v_fmac_f32_e32 v211, v187, v187
	v_fmac_f32_e32 v206, v188, v188
	v_fmac_f32_e32 v207, v189, v189
	v_fmac_f32_e32 v210, v190, v190
	v_fmac_f32_e32 v211, v191, v191
	v_fmac_f32_e32 v206, v192, v192
	v_fmac_f32_e32 v207, v193, v193
	v_fmac_f32_e32 v210, v194, v194
	v_fmac_f32_e32 v211, v195, v195
	v_fmac_f32_e32 v206, v196, v196
	v_fmac_f32_e32 v207, v197, v197
	v_fmac_f32_e32 v210, v198, v198
	v_fmac_f32_e32 v211, v199, v199
	v_fmac_f32_e32 v206, v200, v200
	v_fmac_f32_e32 v207, v201, v201
	v_fmac_f32_e32 v210, v202, v202
	v_fmac_f32_e32 v211, v203, v203
	v_add_f32_e32 v206, v206, v207
	v_add_f32_e32 v210, v210, v211
	v_add_f32_e32 v206, v206, v210
	ds_bpermute_b32 v212, v7, v206
	s_waitcnt lgkmcnt(0)
	v_add_f32_e32 v206, v206, v212
	ds_bpermute_b32 v212, v8, v206
	s_waitcnt lgkmcnt(0)
	v_add_f32_e32 v206, v206, v212
	ds_bpermute_b32 v212, v9, v206
	s_waitcnt lgkmcnt(0)
	v_add_f32_e32 v206, v206, v212
	ds_bpermute_b32 v212, v10, v206
	s_waitcnt lgkmcnt(0)
	v_add_f32_e32 v206, v206, v212
	ds_bpermute_b32 v212, v11, v206
	s_waitcnt lgkmcnt(0)
	v_add_f32_e32 v206, v206, v212
	ds_bpermute_b32 v212, v204, v206
	s_waitcnt lgkmcnt(0)
	v_add_f32_e32 v206, v206, v212
	v_fmamk_f32 v206, v206, 0x3a000000, v205
	v_rsq_f32_e32 v213, v206
	s_nop 0
	v_mul_f32_e32 v172, v172, v213
	v_fmac_f32_e32 v92, v172, v12
	v_mul_f32_e32 v173, v173, v213
	v_fmac_f32_e32 v93, v173, v13
	v_mul_f32_e32 v174, v174, v213
	v_fmac_f32_e32 v94, v174, v14
	v_mul_f32_e32 v175, v175, v213
	v_fmac_f32_e32 v95, v175, v15
	v_mul_f32_e32 v176, v176, v213
	v_fmac_f32_e32 v96, v176, v16
	v_mul_f32_e32 v177, v177, v213
	v_fmac_f32_e32 v97, v177, v17
	v_mul_f32_e32 v178, v178, v213
	v_fmac_f32_e32 v98, v178, v18
	v_mul_f32_e32 v179, v179, v213
	v_fmac_f32_e32 v99, v179, v19
	v_mul_f32_e32 v180, v180, v213
	v_fmac_f32_e32 v100, v180, v20
	v_mul_f32_e32 v181, v181, v213
	v_fmac_f32_e32 v101, v181, v21
	v_mul_f32_e32 v182, v182, v213
	v_fmac_f32_e32 v102, v182, v22
	v_mul_f32_e32 v183, v183, v213
	v_fmac_f32_e32 v103, v183, v23
	v_mul_f32_e32 v184, v184, v213
	v_fmac_f32_e32 v104, v184, v24
	v_mul_f32_e32 v185, v185, v213
	v_fmac_f32_e32 v105, v185, v25
	v_mul_f32_e32 v186, v186, v213
	v_fmac_f32_e32 v106, v186, v26
	v_mul_f32_e32 v187, v187, v213
	v_fmac_f32_e32 v107, v187, v27
	v_mul_f32_e32 v188, v188, v213
	v_fmac_f32_e32 v108, v188, v28
	v_mul_f32_e32 v189, v189, v213
	v_fmac_f32_e32 v109, v189, v29
	v_mul_f32_e32 v190, v190, v213
	v_fmac_f32_e32 v110, v190, v30
	v_mul_f32_e32 v191, v191, v213
	v_fmac_f32_e32 v111, v191, v31
	v_mul_f32_e32 v192, v192, v213
	v_fmac_f32_e32 v112, v192, v32
	v_mul_f32_e32 v193, v193, v213
	v_fmac_f32_e32 v113, v193, v33
	v_mul_f32_e32 v194, v194, v213
	v_fmac_f32_e32 v114, v194, v34
	v_mul_f32_e32 v195, v195, v213
	v_fmac_f32_e32 v115, v195, v35
	v_mul_f32_e32 v196, v196, v213
	v_fmac_f32_e32 v116, v196, v36
	v_mul_f32_e32 v197, v197, v213
	v_fmac_f32_e32 v117, v197, v37
	v_mul_f32_e32 v198, v198, v213
	v_fmac_f32_e32 v118, v198, v38
	v_mul_f32_e32 v199, v199, v213
	v_fmac_f32_e32 v119, v199, v39
	v_mul_f32_e32 v200, v200, v213
	v_fmac_f32_e32 v120, v200, v40
	v_mul_f32_e32 v201, v201, v213
	v_fmac_f32_e32 v121, v201, v41
	v_mul_f32_e32 v202, v202, v213
	v_fmac_f32_e32 v122, v202, v42
	v_mul_f32_e32 v203, v203, v213
	v_fmac_f32_e32 v123, v203, v43
	global_store_dwordx4 v1, v[92:95], s[14:15] sc1
	global_store_dwordx4 v1, v[96:99], s[14:15] offset:16 sc1
	global_store_dwordx4 v1, v[100:103], s[14:15] offset:2048 sc1
	global_store_dwordx4 v1, v[104:107], s[14:15] offset:2064 sc1
	global_store_dwordx4 v2, v[108:111], s[14:15] sc1
	global_store_dwordx4 v2, v[112:115], s[14:15] offset:16 sc1
	global_store_dwordx4 v2, v[116:119], s[14:15] offset:2048 sc1
	global_store_dwordx4 v2, v[120:123], s[14:15] offset:2064 sc1
	v_mul_f32_e32 v206, v92, v92
	v_mul_f32_e32 v207, v93, v93
	v_mul_f32_e32 v210, v94, v94
	v_mul_f32_e32 v211, v95, v95
	v_fmac_f32_e32 v206, v96, v96
	v_fmac_f32_e32 v207, v97, v97
	v_fmac_f32_e32 v210, v98, v98
	v_fmac_f32_e32 v211, v99, v99
	v_fmac_f32_e32 v206, v100, v100
	v_fmac_f32_e32 v207, v101, v101
	v_fmac_f32_e32 v210, v102, v102
	v_fmac_f32_e32 v211, v103, v103
	v_fmac_f32_e32 v206, v104, v104
	v_fmac_f32_e32 v207, v105, v105
	v_fmac_f32_e32 v210, v106, v106
	v_fmac_f32_e32 v211, v107, v107
	v_fmac_f32_e32 v206, v108, v108
	v_fmac_f32_e32 v207, v109, v109
	v_fmac_f32_e32 v210, v110, v110
	v_fmac_f32_e32 v211, v111, v111
	v_fmac_f32_e32 v206, v112, v112
	v_fmac_f32_e32 v207, v113, v113
	v_fmac_f32_e32 v210, v114, v114
	v_fmac_f32_e32 v211, v115, v115
	v_fmac_f32_e32 v206, v116, v116
	v_fmac_f32_e32 v207, v117, v117
	v_fmac_f32_e32 v210, v118, v118
	v_fmac_f32_e32 v211, v119, v119
	v_fmac_f32_e32 v206, v120, v120
	v_fmac_f32_e32 v207, v121, v121
	v_fmac_f32_e32 v210, v122, v122
	v_fmac_f32_e32 v211, v123, v123
	v_add_f32_e32 v206, v206, v207
	v_add_f32_e32 v210, v210, v211
	v_add_f32_e32 v206, v206, v210
	ds_bpermute_b32 v212, v7, v206
	s_waitcnt lgkmcnt(0)
	v_add_f32_e32 v206, v206, v212
	ds_bpermute_b32 v212, v8, v206
	s_waitcnt lgkmcnt(0)
	v_add_f32_e32 v206, v206, v212
	ds_bpermute_b32 v212, v9, v206
	s_waitcnt lgkmcnt(0)
	v_add_f32_e32 v206, v206, v212
	ds_bpermute_b32 v212, v10, v206
	s_waitcnt lgkmcnt(0)
	v_add_f32_e32 v206, v206, v212
	ds_bpermute_b32 v212, v11, v206
	s_waitcnt lgkmcnt(0)
	v_add_f32_e32 v206, v206, v212
	ds_bpermute_b32 v212, v204, v206
	s_waitcnt lgkmcnt(0)
	v_add_f32_e32 v206, v206, v212
	v_fmamk_f32 v206, v206, 0x3a000000, v205
	v_rsq_f32_e32 v213, v206
	s_nop 0
	v_mul_f32_e32 v172, v92, v213
	v_mul_f32_e32 v172, v172, v44
	v_mul_f32_e32 v173, v93, v213
	v_mul_f32_e32 v173, v173, v45
	v_mul_f32_e32 v174, v94, v213
	v_mul_f32_e32 v174, v174, v46
	v_mul_f32_e32 v175, v95, v213
	v_mul_f32_e32 v175, v175, v47
	v_mul_f32_e32 v176, v96, v213
	v_mul_f32_e32 v176, v176, v48
	v_mul_f32_e32 v177, v97, v213
	v_mul_f32_e32 v177, v177, v49
	v_mul_f32_e32 v178, v98, v213
	v_mul_f32_e32 v178, v178, v50
	v_mul_f32_e32 v179, v99, v213
	v_mul_f32_e32 v179, v179, v51
	v_mul_f32_e32 v180, v100, v213
	v_mul_f32_e32 v180, v180, v52
	v_mul_f32_e32 v181, v101, v213
	v_mul_f32_e32 v181, v181, v53
	v_mul_f32_e32 v182, v102, v213
	v_mul_f32_e32 v182, v182, v54
	v_mul_f32_e32 v183, v103, v213
	v_mul_f32_e32 v183, v183, v55
	v_mul_f32_e32 v184, v104, v213
	v_mul_f32_e32 v184, v184, v56
	v_mul_f32_e32 v185, v105, v213
	v_mul_f32_e32 v185, v185, v57
	v_mul_f32_e32 v186, v106, v213
	v_mul_f32_e32 v186, v186, v58
	v_mul_f32_e32 v187, v107, v213
	v_mul_f32_e32 v187, v187, v59
	v_mul_f32_e32 v188, v108, v213
	v_mul_f32_e32 v188, v188, v60
	v_mul_f32_e32 v189, v109, v213
	v_mul_f32_e32 v189, v189, v61
	v_mul_f32_e32 v190, v110, v213
	v_mul_f32_e32 v190, v190, v62
	v_mul_f32_e32 v191, v111, v213
	v_mul_f32_e32 v191, v191, v63
	v_mul_f32_e32 v192, v112, v213
	v_mul_f32_e32 v192, v192, v64
	v_mul_f32_e32 v193, v113, v213
	v_mul_f32_e32 v193, v193, v65
	v_mul_f32_e32 v194, v114, v213
	v_mul_f32_e32 v194, v194, v66
	v_mul_f32_e32 v195, v115, v213
	v_mul_f32_e32 v195, v195, v67
	v_mul_f32_e32 v196, v116, v213
	v_mul_f32_e32 v196, v196, v68
	v_mul_f32_e32 v197, v117, v213
	v_mul_f32_e32 v197, v197, v69
	v_mul_f32_e32 v198, v118, v213
	v_mul_f32_e32 v198, v198, v70
	v_mul_f32_e32 v199, v119, v213
	v_mul_f32_e32 v199, v199, v71
	v_mul_f32_e32 v200, v120, v213
	v_mul_f32_e32 v200, v200, v72
	v_mul_f32_e32 v201, v121, v213
	v_mul_f32_e32 v201, v201, v73
	v_mul_f32_e32 v202, v122, v213
	v_mul_f32_e32 v202, v202, v74
	v_mul_f32_e32 v203, v123, v213
	v_mul_f32_e32 v203, v203, v75
	v_cvt_pk_bf16_f32 v76, v172, v173
	v_cvt_pk_bf16_f32 v77, v174, v175
	v_cvt_pk_bf16_f32 v78, v176, v177
	v_cvt_pk_bf16_f32 v79, v178, v179
	v_cvt_pk_bf16_f32 v80, v180, v181
	v_cvt_pk_bf16_f32 v81, v182, v183
	v_cvt_pk_bf16_f32 v82, v184, v185
	v_cvt_pk_bf16_f32 v83, v186, v187
	v_cvt_pk_bf16_f32 v84, v188, v189
	v_cvt_pk_bf16_f32 v85, v190, v191
	v_cvt_pk_bf16_f32 v86, v192, v193
	v_cvt_pk_bf16_f32 v87, v194, v195
	v_cvt_pk_bf16_f32 v88, v196, v197
	v_cvt_pk_bf16_f32 v89, v198, v199
	v_cvt_pk_bf16_f32 v90, v200, v201
	v_cvt_pk_bf16_f32 v91, v202, v203
	global_store_dwordx4 v0, v[76:79], s[16:17] sc1
	global_store_dwordx4 v0, v[80:83], s[16:17] offset:1024 sc1
	global_store_dwordx4 v0, v[84:87], s[16:17] offset:2048 sc1
	global_store_dwordx4 v0, v[88:91], s[16:17] offset:3072 sc1
	s_mov_b32 s2, s29
	s_cmp_ge_u32 s2, 0x2080
	s_cbranch_scc1 .Lp6_tail

.Lp6_B_nopf:
	s_lshl_b32 s4, s2, 12
	s_add_u32 s16, s26, s4
	s_addc_u32 s17, s27, 0
	s_lshl_b32 s4, s2, 13
	s_add_u32 s14, s22, s4
	s_addc_u32 s15, s23, 0
	v_lshlrev_b32_e32 v172, 16, v124
	v_and_b32_e32 v173, 0xffff0000, v124
	v_lshlrev_b32_e32 v174, 16, v125
	v_and_b32_e32 v175, 0xffff0000, v125
	v_lshlrev_b32_e32 v176, 16, v126
	v_and_b32_e32 v177, 0xffff0000, v126
	v_lshlrev_b32_e32 v178, 16, v127
	v_and_b32_e32 v179, 0xffff0000, v127
	v_lshlrev_b32_e32 v180, 16, v128
	v_and_b32_e32 v181, 0xffff0000, v128
	v_lshlrev_b32_e32 v182, 16, v129
	v_and_b32_e32 v183, 0xffff0000, v129
	v_lshlrev_b32_e32 v184, 16, v130
	v_and_b32_e32 v185, 0xffff0000, v130
	v_lshlrev_b32_e32 v186, 16, v131
	v_and_b32_e32 v187, 0xffff0000, v131
	v_lshlrev_b32_e32 v188, 16, v132
	v_and_b32_e32 v189, 0xffff0000, v132
	v_lshlrev_b32_e32 v190, 16, v133
	v_and_b32_e32 v191, 0xffff0000, v133
	v_lshlrev_b32_e32 v192, 16, v134
	v_and_b32_e32 v193, 0xffff0000, v134
	v_lshlrev_b32_e32 v194, 16, v135
	v_and_b32_e32 v195, 0xffff0000, v135
	v_lshlrev_b32_e32 v196, 16, v136
	v_and_b32_e32 v197, 0xffff0000, v136
	v_lshlrev_b32_e32 v198, 16, v137
	v_and_b32_e32 v199, 0xffff0000, v137
	v_lshlrev_b32_e32 v200, 16, v138
	v_and_b32_e32 v201, 0xffff0000, v138
	v_lshlrev_b32_e32 v202, 16, v139
	v_and_b32_e32 v203, 0xffff0000, v139
	v_mul_f32_e32 v206, v172, v172
	v_mul_f32_e32 v207, v173, v173
	v_mul_f32_e32 v210, v174, v174
	v_mul_f32_e32 v211, v175, v175
	v_fmac_f32_e32 v206, v176, v176
	v_fmac_f32_e32 v207, v177, v177
	v_fmac_f32_e32 v210, v178, v178
	v_fmac_f32_e32 v211, v179, v179
	v_fmac_f32_e32 v206, v180, v180
	v_fmac_f32_e32 v207, v181, v181
	v_fmac_f32_e32 v210, v182, v182
	v_fmac_f32_e32 v211, v183, v183
	v_fmac_f32_e32 v206, v184, v184
	v_fmac_f32_e32 v207, v185, v185
	v_fmac_f32_e32 v210, v186, v186
	v_fmac_f32_e32 v211, v187, v187
	v_fmac_f32_e32 v206, v188, v188
	v_fmac_f32_e32 v207, v189, v189
	v_fmac_f32_e32 v210, v190, v190
	v_fmac_f32_e32 v211, v191, v191
	v_fmac_f32_e32 v206, v192, v192
	v_fmac_f32_e32 v207, v193, v193
	v_fmac_f32_e32 v210, v194, v194
	v_fmac_f32_e32 v211, v195, v195
	v_fmac_f32_e32 v206, v196, v196
	v_fmac_f32_e32 v207, v197, v197
	v_fmac_f32_e32 v210, v198, v198
	v_fmac_f32_e32 v211, v199, v199
	v_fmac_f32_e32 v206, v200, v200
	v_fmac_f32_e32 v207, v201, v201
	v_fmac_f32_e32 v210, v202, v202
	v_fmac_f32_e32 v211, v203, v203
	v_add_f32_e32 v206, v206, v207
	v_add_f32_e32 v210, v210, v211
	v_add_f32_e32 v206, v206, v210
	ds_bpermute_b32 v212, v7, v206
	s_waitcnt lgkmcnt(0)
	v_add_f32_e32 v206, v206, v212
	ds_bpermute_b32 v212, v8, v206
	s_waitcnt lgkmcnt(0)
	v_add_f32_e32 v206, v206, v212
	ds_bpermute_b32 v212, v9, v206
	s_waitcnt lgkmcnt(0)
	v_add_f32_e32 v206, v206, v212
	ds_bpermute_b32 v212, v10, v206
	s_waitcnt lgkmcnt(0)
	v_add_f32_e32 v206, v206, v212
	ds_bpermute_b32 v212, v11, v206
	s_waitcnt lgkmcnt(0)
	v_add_f32_e32 v206, v206, v212
	ds_bpermute_b32 v212, v204, v206
	s_waitcnt lgkmcnt(0)
	v_add_f32_e32 v206, v206, v212
	v_fmamk_f32 v206, v206, 0x3a000000, v205
	v_rsq_f32_e32 v213, v206
	s_nop 0
	v_mul_f32_e32 v172, v172, v213
	v_fmac_f32_e32 v140, v172, v12
	v_mul_f32_e32 v173, v173, v213
	v_fmac_f32_e32 v141, v173, v13
	v_mul_f32_e32 v174, v174, v213
	v_fmac_f32_e32 v142, v174, v14
	v_mul_f32_e32 v175, v175, v213
	v_fmac_f32_e32 v143, v175, v15
	v_mul_f32_e32 v176, v176, v213
	v_fmac_f32_e32 v144, v176, v16
	v_mul_f32_e32 v177, v177, v213
	v_fmac_f32_e32 v145, v177, v17
	v_mul_f32_e32 v178, v178, v213
	v_fmac_f32_e32 v146, v178, v18
	v_mul_f32_e32 v179, v179, v213
	v_fmac_f32_e32 v147, v179, v19
	v_mul_f32_e32 v180, v180, v213
	v_fmac_f32_e32 v148, v180, v20
	v_mul_f32_e32 v181, v181, v213
	v_fmac_f32_e32 v149, v181, v21
	v_mul_f32_e32 v182, v182, v213
	v_fmac_f32_e32 v150, v182, v22
	v_mul_f32_e32 v183, v183, v213
	v_fmac_f32_e32 v151, v183, v23
	v_mul_f32_e32 v184, v184, v213
	v_fmac_f32_e32 v152, v184, v24
	v_mul_f32_e32 v185, v185, v213
	v_fmac_f32_e32 v153, v185, v25
	v_mul_f32_e32 v186, v186, v213
	v_fmac_f32_e32 v154, v186, v26
	v_mul_f32_e32 v187, v187, v213
	v_fmac_f32_e32 v155, v187, v27
	v_mul_f32_e32 v188, v188, v213
	v_fmac_f32_e32 v156, v188, v28
	v_mul_f32_e32 v189, v189, v213
	v_fmac_f32_e32 v157, v189, v29
	v_mul_f32_e32 v190, v190, v213
	v_fmac_f32_e32 v158, v190, v30
	v_mul_f32_e32 v191, v191, v213
	v_fmac_f32_e32 v159, v191, v31
	v_mul_f32_e32 v192, v192, v213
	v_fmac_f32_e32 v160, v192, v32
	v_mul_f32_e32 v193, v193, v213
	v_fmac_f32_e32 v161, v193, v33
	v_mul_f32_e32 v194, v194, v213
	v_fmac_f32_e32 v162, v194, v34
	v_mul_f32_e32 v195, v195, v213
	v_fmac_f32_e32 v163, v195, v35
	v_mul_f32_e32 v196, v196, v213
	v_fmac_f32_e32 v164, v196, v36
	v_mul_f32_e32 v197, v197, v213
	v_fmac_f32_e32 v165, v197, v37
	v_mul_f32_e32 v198, v198, v213
	v_fmac_f32_e32 v166, v198, v38
	v_mul_f32_e32 v199, v199, v213
	v_fmac_f32_e32 v167, v199, v39
	v_mul_f32_e32 v200, v200, v213
	v_fmac_f32_e32 v168, v200, v40
	v_mul_f32_e32 v201, v201, v213
	v_fmac_f32_e32 v169, v201, v41
	v_mul_f32_e32 v202, v202, v213
	v_fmac_f32_e32 v170, v202, v42
	v_mul_f32_e32 v203, v203, v213
	v_fmac_f32_e32 v171, v203, v43
	global_store_dwordx4 v1, v[140:143], s[14:15] sc1
	global_store_dwordx4 v1, v[144:147], s[14:15] offset:16 sc1
	global_store_dwordx4 v1, v[148:151], s[14:15] offset:2048 sc1
	global_store_dwordx4 v1, v[152:155], s[14:15] offset:2064 sc1
	global_store_dwordx4 v2, v[156:159], s[14:15] sc1
	global_store_dwordx4 v2, v[160:163], s[14:15] offset:16 sc1
	global_store_dwordx4 v2, v[164:167], s[14:15] offset:2048 sc1
	global_store_dwordx4 v2, v[168:171], s[14:15] offset:2064 sc1
	v_mul_f32_e32 v206, v140, v140
	v_mul_f32_e32 v207, v141, v141
	v_mul_f32_e32 v210, v142, v142
	v_mul_f32_e32 v211, v143, v143
	v_fmac_f32_e32 v206, v144, v144
	v_fmac_f32_e32 v207, v145, v145
	v_fmac_f32_e32 v210, v146, v146
	v_fmac_f32_e32 v211, v147, v147
	v_fmac_f32_e32 v206, v148, v148
	v_fmac_f32_e32 v207, v149, v149
	v_fmac_f32_e32 v210, v150, v150
	v_fmac_f32_e32 v211, v151, v151
	v_fmac_f32_e32 v206, v152, v152
	v_fmac_f32_e32 v207, v153, v153
	v_fmac_f32_e32 v210, v154, v154
	v_fmac_f32_e32 v211, v155, v155
	v_fmac_f32_e32 v206, v156, v156
	v_fmac_f32_e32 v207, v157, v157
	v_fmac_f32_e32 v210, v158, v158
	v_fmac_f32_e32 v211, v159, v159
	v_fmac_f32_e32 v206, v160, v160
	v_fmac_f32_e32 v207, v161, v161
	v_fmac_f32_e32 v210, v162, v162
	v_fmac_f32_e32 v211, v163, v163
	v_fmac_f32_e32 v206, v164, v164
	v_fmac_f32_e32 v207, v165, v165
	v_fmac_f32_e32 v210, v166, v166
	v_fmac_f32_e32 v211, v167, v167
	v_fmac_f32_e32 v206, v168, v168
	v_fmac_f32_e32 v207, v169, v169
	v_fmac_f32_e32 v210, v170, v170
	v_fmac_f32_e32 v211, v171, v171
	v_add_f32_e32 v206, v206, v207
	v_add_f32_e32 v210, v210, v211
	v_add_f32_e32 v206, v206, v210
	ds_bpermute_b32 v212, v7, v206
	s_waitcnt lgkmcnt(0)
	v_add_f32_e32 v206, v206, v212
	ds_bpermute_b32 v212, v8, v206
	s_waitcnt lgkmcnt(0)
	v_add_f32_e32 v206, v206, v212
	ds_bpermute_b32 v212, v9, v206
	s_waitcnt lgkmcnt(0)
	v_add_f32_e32 v206, v206, v212
	ds_bpermute_b32 v212, v10, v206
	s_waitcnt lgkmcnt(0)
	v_add_f32_e32 v206, v206, v212
	ds_bpermute_b32 v212, v11, v206
	s_waitcnt lgkmcnt(0)
	v_add_f32_e32 v206, v206, v212
	ds_bpermute_b32 v212, v204, v206
	s_waitcnt lgkmcnt(0)
	v_add_f32_e32 v206, v206, v212
	v_fmamk_f32 v206, v206, 0x3a000000, v205
	v_rsq_f32_e32 v213, v206
	s_nop 0
	v_mul_f32_e32 v172, v140, v213
	v_mul_f32_e32 v172, v172, v44
	v_mul_f32_e32 v173, v141, v213
	v_mul_f32_e32 v173, v173, v45
	v_mul_f32_e32 v174, v142, v213
	v_mul_f32_e32 v174, v174, v46
	v_mul_f32_e32 v175, v143, v213
	v_mul_f32_e32 v175, v175, v47
	v_mul_f32_e32 v176, v144, v213
	v_mul_f32_e32 v176, v176, v48
	v_mul_f32_e32 v177, v145, v213
	v_mul_f32_e32 v177, v177, v49
	v_mul_f32_e32 v178, v146, v213
	v_mul_f32_e32 v178, v178, v50
	v_mul_f32_e32 v179, v147, v213
	v_mul_f32_e32 v179, v179, v51
	v_mul_f32_e32 v180, v148, v213
	v_mul_f32_e32 v180, v180, v52
	v_mul_f32_e32 v181, v149, v213
	v_mul_f32_e32 v181, v181, v53
	v_mul_f32_e32 v182, v150, v213
	v_mul_f32_e32 v182, v182, v54
	v_mul_f32_e32 v183, v151, v213
	v_mul_f32_e32 v183, v183, v55
	v_mul_f32_e32 v184, v152, v213
	v_mul_f32_e32 v184, v184, v56
	v_mul_f32_e32 v185, v153, v213
	v_mul_f32_e32 v185, v185, v57
	v_mul_f32_e32 v186, v154, v213
	v_mul_f32_e32 v186, v186, v58
	v_mul_f32_e32 v187, v155, v213
	v_mul_f32_e32 v187, v187, v59
	v_mul_f32_e32 v188, v156, v213
	v_mul_f32_e32 v188, v188, v60
	v_mul_f32_e32 v189, v157, v213
	v_mul_f32_e32 v189, v189, v61
	v_mul_f32_e32 v190, v158, v213
	v_mul_f32_e32 v190, v190, v62
	v_mul_f32_e32 v191, v159, v213
	v_mul_f32_e32 v191, v191, v63
	v_mul_f32_e32 v192, v160, v213
	v_mul_f32_e32 v192, v192, v64
	v_mul_f32_e32 v193, v161, v213
	v_mul_f32_e32 v193, v193, v65
	v_mul_f32_e32 v194, v162, v213
	v_mul_f32_e32 v194, v194, v66
	v_mul_f32_e32 v195, v163, v213
	v_mul_f32_e32 v195, v195, v67
	v_mul_f32_e32 v196, v164, v213
	v_mul_f32_e32 v196, v196, v68
	v_mul_f32_e32 v197, v165, v213
	v_mul_f32_e32 v197, v197, v69
	v_mul_f32_e32 v198, v166, v213
	v_mul_f32_e32 v198, v198, v70
	v_mul_f32_e32 v199, v167, v213
	v_mul_f32_e32 v199, v199, v71
	v_mul_f32_e32 v200, v168, v213
	v_mul_f32_e32 v200, v200, v72
	v_mul_f32_e32 v201, v169, v213
	v_mul_f32_e32 v201, v201, v73
	v_mul_f32_e32 v202, v170, v213
	v_mul_f32_e32 v202, v202, v74
	v_mul_f32_e32 v203, v171, v213
	v_mul_f32_e32 v203, v203, v75
	v_cvt_pk_bf16_f32 v124, v172, v173
	v_cvt_pk_bf16_f32 v125, v174, v175
	v_cvt_pk_bf16_f32 v126, v176, v177
	v_cvt_pk_bf16_f32 v127, v178, v179
	v_cvt_pk_bf16_f32 v128, v180, v181
	v_cvt_pk_bf16_f32 v129, v182, v183
	v_cvt_pk_bf16_f32 v130, v184, v185
	v_cvt_pk_bf16_f32 v131, v186, v187
	v_cvt_pk_bf16_f32 v132, v188, v189
	v_cvt_pk_bf16_f32 v133, v190, v191
	v_cvt_pk_bf16_f32 v134, v192, v193
	v_cvt_pk_bf16_f32 v135, v194, v195
	v_cvt_pk_bf16_f32 v136, v196, v197
	v_cvt_pk_bf16_f32 v137, v198, v199
	v_cvt_pk_bf16_f32 v138, v200, v201
	v_cvt_pk_bf16_f32 v139, v202, v203
	global_store_dwordx4 v0, v[124:127], s[16:17] sc1
	global_store_dwordx4 v0, v[128:131], s[16:17] offset:1024 sc1
	global_store_dwordx4 v0, v[132:135], s[16:17] offset:2048 sc1
	global_store_dwordx4 v0, v[136:139], s[16:17] offset:3072 sc1
	s_mov_b32 s2, s29
	s_cmp_ge_u32 s2, 0x2080
	s_cbranch_scc0 .Lp6_A
.Lp6_tail:
	s_cmp_ge_u32 s2, 0x2100
	s_cbranch_scc1 .Lp6_done
	s_lshl_b32 s4, s2, 12
	s_add_u32 s16, s26, s4
	s_addc_u32 s17, s27, 0
	global_store_dwordx2 v5, v[214:215], s[16:17] sc1
	global_store_dwordx2 v5, v[214:215], s[16:17] offset:512 sc1
	global_store_dwordx2 v5, v[214:215], s[16:17] offset:1024 sc1
	global_store_dwordx2 v5, v[214:215], s[16:17] offset:1536 sc1
	global_store_dwordx2 v5, v[214:215], s[16:17] offset:2048 sc1
	global_store_dwordx2 v5, v[214:215], s[16:17] offset:2560 sc1
	global_store_dwordx2 v5, v[214:215], s[16:17] offset:3072 sc1
	global_store_dwordx2 v5, v[214:215], s[16:17] offset:3584 sc1
	s_add_u32 s2, s2, s3
	s_branch .Lp6_tail
